# speedup vs baseline: 1.0371x; 1.0008x over previous
.LBB0_496:
	s_cbranch_execz .LBB0_484
	v_readlane_b32 s34, v252, 16
	v_readlane_b32 s35, v252, 17
	s_cmp_lt_i32 s35, 4
	s_cbranch_scc1 .LBB0_536
	s_waitcnt vmcnt(0)
	v_cmp_eq_u32_e32 vcc, 0, v1
	s_waitcnt vmcnt(0)
	s_barrier
	s_and_saveexec_b64 s[0:1], vcc
	s_cbranch_execz .LBB0_535
	s_cmp_lg_u32 s101, 0
	s_cbranch_scc1 .Lxl_glob_3
	s_and_b32 s6, s2, 7
	v_mov_b32_e32 v2, 0
	v_mov_b32_e32 v3, 1
	s_nop 3
	s_lshl_b32 s3, s6, 8
	s_add_u32 s4, s86, s3
	s_addc_u32 s5, s87, 0
	s_add_u32 s4, s4, 0x2b00498
	s_addc_u32 s5, s5, 0
	s_mov_b32 s98, 0
	global_atomic_add v2, v3, s[4:5]

.LBB0_590:
	s_cmp_gt_i32 s34, 5
	s_cselect_b64 s[0:1], -1, 0
	s_cmp_lt_i32 s35, 5
	s_cselect_b64 s[4:5], -1, 0
	s_or_b64 s[0:1], s[0:1], s[4:5]
	s_and_b64 vcc, exec, s[0:1]
	s_cbranch_vccnz .LBB0_660
	s_mov_b64 s[0:1], 0
	s_add_u32 s0, s86, s0
	s_load_dword s3, s[92:93], 0xd8
	s_addc_u32 s1, s87, s1
	s_add_u32 s4, s0, 0x6c00000
	s_addc_u32 s5, s1, 0
	s_add_u32 s6, s0, 0x2810000
	s_addc_u32 s7, s1, 0
	s_waitcnt lgkmcnt(0)
	s_and_b32 s8, s3, 7
	s_cmp_lg_u32 s8, 0
	s_cselect_b64 s[10:11], -1, 0
	s_cmp_lt_i32 s3, 8
	s_cselect_b64 s[12:13], -1, 0
	s_lshl_b32 s8, s2, 5
	s_or_b64 s[10:11], s[12:13], s[10:11]
	s_lshr_b32 s33, s3, 3
	s_ashr_i32 s48, s2, 3
	s_and_b32 s49, s8, 0xe0
	s_add_u32 s50, s0, 0x2c00000
	s_addc_u32 s51, s1, 0
	s_add_u32 s54, s0, 0x600000
	v_mbcnt_lo_u32_b32 v2, -1, 0
	s_mov_b32 s9, 0
	s_addc_u32 s55, s1, 0
	v_and_b32_e32 v1, 0x3ff, v0
	s_movk_i32 s56, 0x100
	v_mov_b32_e32 v131, 0
	s_add_i32 s57, 0, 0x10000
	s_add_i32 s60, 0, 0x14000
	s_mov_b64 s[12:13], 0x80
	s_add_i32 s61, 0, 0x18000
	s_add_i32 s62, 0, 0x1c000
	s_movk_i32 s63, 0x3c0
	s_mov_b64 s[14:15], 0x2c40080
	s_mov_b64 s[16:17], 0x600100
	s_mov_b64 s[18:19], 0x2c00100
	s_mov_b64 s[20:21], 0x640100
	s_mov_b64 s[22:23], 0x2c40100
	s_mov_b64 s[24:25], 0x600180
	s_mov_b64 s[26:27], 0x2c00180
	s_mov_b64 s[28:29], 0x640180
	s_mov_b64 s[30:31], 0x780
	v_mov_b32_e32 v144, 1
	v_mbcnt_hi_u32_b32 v145, -1, v2
	s_mov_b32 s64, 0
	s_waitcnt vmcnt(0)
	s_branch .LBB0_593

.LBB0_660:
	s_cmp_gt_i32 s34, 6
	s_cselect_b64 s[0:1], -1, 0
	s_cmp_lt_i32 s35, 6
	s_cselect_b64 s[4:5], -1, 0
	s_or_b64 s[0:1], s[0:1], s[4:5]
	s_and_b64 vcc, exec, s[0:1]
	s_cbranch_vccnz .LBB0_708
	s_mov_b64 s[0:1], 0
	s_load_dword s3, s[92:93], 0xd8
	s_add_u32 s8, s86, s0
	s_addc_u32 s9, s87, s1
	v_and_b32_e32 v1, 0x3ff, v0
	v_mov_b32_e32 v4, 0x358637bd
	s_waitcnt lgkmcnt(0)
	s_and_b32 s0, s3, 7
	s_cmp_lg_u32 s0, 0
	s_cselect_b64 s[0:1], -1, 0
	s_cmp_lt_i32 s3, 8
	s_cselect_b64 s[4:5], -1, 0
	s_or_b64 s[0:1], s[4:5], s[0:1]
	s_lshl_b32 s4, s2, 8
	s_lshr_b32 s12, s3, 3
	s_ashr_i32 s14, s2, 3
	s_and_b32 s13, s4, 0x700
	s_add_u32 s4, s8, 0x6c00000
	s_addc_u32 s5, s9, 0
	s_add_u32 s6, s8, 0x2810000
	s_addc_u32 s7, s9, 0
	s_add_u32 s8, s8, 0xac00000
	s_addc_u32 s9, s9, 0
	s_mov_b32 s15, 0x800000
	v_mov_b32_e32 v3, 0
	s_mov_b32 s16, s2
	s_branch .LBB0_663

.LBB0_708:
	s_cmp_gt_i32 s34, 7
	s_cselect_b64 s[0:1], -1, 0
	s_cmp_lt_i32 s35, 7
	s_cselect_b64 s[4:5], -1, 0
	s_or_b64 s[0:1], s[0:1], s[4:5]
	s_and_b64 vcc, exec, s[0:1]
	s_cbranch_vccnz .LBB0_778
	s_mov_b64 s[0:1], 0
	s_add_u32 s6, s86, s0
	s_addc_u32 s7, s87, s1
	s_add_u32 s8, s6, 0x2810000
	s_addc_u32 s9, s7, 0
	s_add_u32 s10, s6, 0x6c00000
	s_addc_u32 s11, s7, 0
	s_add_u32 s12, s6, 0x8c00000
	s_load_dword s3, s[92:93], 0xd8
	s_addc_u32 s13, s7, 0
	s_add_u32 s14, s6, 0x6c00000
	s_addc_u32 s15, s7, 0
	s_add_u32 s16, s6, 0x2820000
	s_addc_u32 s17, s7, 0
	s_waitcnt lgkmcnt(0)
	s_and_b32 s0, s3, 7
	s_cmp_lg_u32 s0, 0
	s_cselect_b64 s[0:1], -1, 0
	s_cmp_lt_i32 s3, 8
	s_cselect_b64 s[4:5], -1, 0
	s_or_b64 s[20:21], s[4:5], s[0:1]
	s_lshl_b32 s0, s2, 5
	s_lshr_b32 s33, s3, 3
	s_ashr_i32 s56, s2, 3
	s_and_b32 s57, s0, 0xe0
	s_add_u32 s60, s6, 0xac00000
	s_addc_u32 s61, s7, 0
	s_add_u32 s62, s6, 0x800000
	v_mbcnt_lo_u32_b32 v2, -1, 0
	s_mov_b32 s19, 0
	s_addc_u32 s63, s7, 0
	v_and_b32_e32 v1, 0x3ff, v0
	s_movk_i32 s64, 0x100
	v_mov_b32_e32 v175, 0
	s_add_i32 s65, 0, 0x10000
	s_add_i32 s66, 0, 0x14000
	s_mov_b64 s[22:23], 0x80
	s_add_i32 s67, 0, 0x18000
	s_add_i32 s68, 0, 0x1c000
	s_movk_i32 s69, 0x3c0
	s_mov_b64 s[24:25], 0xac40080
	s_mov_b64 s[26:27], 0x800100
	s_mov_b64 s[28:29], 0xac00100
	s_mov_b64 s[30:31], 0x840100
	s_mov_b64 s[36:37], 0xac40100
	s_mov_b64 s[38:39], 0x800180
	s_mov_b64 s[40:41], 0xac00180
	s_mov_b64 s[44:45], 0x840180
	s_mov_b64 s[46:47], 0x780
	v_mov_b32_e32 v180, 0x358637bd
	s_mov_b32 s70, 0x800000
	v_mov_b32_e32 v181, 1
	v_mbcnt_hi_u32_b32 v182, -1, v2
	s_mov_b32 s71, 0
	s_branch .LBB0_711

.LBB0_1027:
	v_readlane_b32 s34, v252, 16
	v_readlane_b32 s35, v252, 17
	s_cmp_lt_i32 s35, 10
	s_cbranch_scc1 .LBB0_1066
	s_waitcnt vmcnt(0)
	v_cmp_eq_u32_e32 vcc, 0, v1
	s_waitcnt vmcnt(0)
	s_barrier
	s_and_saveexec_b64 s[0:1], vcc
	s_cbranch_execz .LBB0_1065
	s_cmp_lg_u32 s101, 0
	s_cbranch_scc1 .Lxl_glob_9
	s_and_b32 s6, s2, 7
	v_mov_b32_e32 v2, 0
	v_mov_b32_e32 v3, 1
	s_nop 3
	s_lshl_b32 s3, s6, 8
	s_add_u32 s4, s86, s3
	s_addc_u32 s5, s87, 0
	s_add_u32 s4, s4, 0x2b0049c
	s_addc_u32 s5, s5, 0
	s_mov_b32 s98, 0
	global_atomic_add v2, v3, s[4:5]

.LBB0_1066:
	s_cmp_gt_i32 s34, 10
	s_cselect_b64 s[0:1], -1, 0
	s_cmp_lt_i32 s35, 10
	s_cselect_b64 s[4:5], -1, 0
	s_or_b64 s[0:1], s[0:1], s[4:5]
	s_and_b64 vcc, exec, s[0:1]
	s_cbranch_vccnz .LBB0_1144
	s_mov_b64 s[0:1], 0
	s_load_dword s3, s[92:93], 0xd8
	s_add_u32 s6, s86, s0
	s_addc_u32 s7, s87, s1
	v_mbcnt_lo_u32_b32 v2, -1, 0
	s_mov_b32 s5, 0
	s_waitcnt lgkmcnt(0)
	s_and_b32 s0, s3, 7
	s_cmp_lg_u32 s0, 0
	s_cselect_b64 s[0:1], -1, 0
	s_cmp_lt_i32 s3, 8
	s_cselect_b64 s[8:9], -1, 0
	s_or_b64 s[8:9], s[8:9], s[0:1]
	s_lshl_b32 s0, s2, 6
	s_lshr_b32 s33, s3, 3
	s_ashr_i32 s48, s2, 3
	s_and_b32 s49, s0, 0x1c0
	s_add_u32 s10, s6, 0x4c00000
	s_addc_u32 s11, s7, 0
	s_add_u32 s50, s6, 0x2000000
	s_addc_u32 s51, s7, 0
	s_add_u32 s52, s6, 0xc80000
	s_addc_u32 s53, s7, 0
	s_add_u32 s12, s6, 0xac00000
	s_addc_u32 s13, s7, 0
	s_add_u32 s14, s6, 0x2830000
	s_addc_u32 s15, s7, 0
	s_add_u32 s54, s6, 0x6c00000
	s_addc_u32 s55, s7, 0
	s_add_u32 s56, s6, 0x1500000
	v_and_b32_e32 v1, 0x3ff, v0
	s_addc_u32 s57, s7, 0
	s_mov_b32 s58, 0x7fffe0
	v_mov_b32_e32 v131, 0
	s_add_i32 s59, 0, 0x10000
	s_add_i32 s60, 0, 0x14000
	s_mov_b64 s[16:17], 0x80
	s_add_i32 s61, 0, 0x18000
	s_add_i32 s62, 0, 0x1c000
	s_mov_b64 s[18:19], 0x100
	s_mov_b64 s[20:21], 0x180
	s_movk_i32 s63, 0x3c0
	s_movk_i32 s64, 0x100
	s_mov_b64 s[22:23], 0x6c40080
	s_mov_b64 s[24:25], 0x1500100
	s_mov_b64 s[26:27], 0x6c00100
	s_mov_b64 s[28:29], 0x1540100
	s_mov_b64 s[30:31], 0x6c40100
	s_mov_b64 s[36:37], 0x1500180
	s_mov_b64 s[38:39], 0x6c00180
	s_mov_b64 s[40:41], 0x1540180
	s_mov_b64 s[44:45], 0x780
	v_mov_b32_e32 v144, 1
	v_mbcnt_hi_u32_b32 v145, -1, v2
	s_mov_b32 s65, 0
	s_waitcnt vmcnt(0)
	s_branch .LBB0_1070

.LBB0_1144:
	s_cmp_gt_i32 s34, 11
	s_cselect_b64 s[0:1], -1, 0
	s_cmp_lt_i32 s35, 11
	s_cselect_b64 s[4:5], -1, 0
	s_or_b64 s[0:1], s[0:1], s[4:5]
	s_and_b64 vcc, exec, s[0:1]
	s_cbranch_vccnz .LBB0_1192
	s_mov_b64 s[0:1], 0
	s_load_dword s3, s[92:93], 0xd8
	s_add_u32 s8, s86, s0
	s_addc_u32 s9, s87, s1
	v_and_b32_e32 v1, 0x3ff, v0
	v_mov_b32_e32 v4, 0x358637bd
	s_waitcnt lgkmcnt(0)
	s_and_b32 s0, s3, 7
	s_cmp_lg_u32 s0, 0
	s_cselect_b64 s[0:1], -1, 0
	s_cmp_lt_i32 s3, 8
	s_cselect_b64 s[4:5], -1, 0
	s_or_b64 s[0:1], s[4:5], s[0:1]
	s_lshl_b32 s4, s2, 8
	s_lshr_b32 s12, s3, 3
	s_ashr_i32 s14, s2, 3
	s_and_b32 s13, s4, 0x700
	s_add_u32 s4, s8, 0xac00000
	s_addc_u32 s5, s9, 0
	s_add_u32 s6, s8, 0x2830000
	s_addc_u32 s7, s9, 0
	s_add_u32 s8, s8, 0x6c00000
	s_addc_u32 s9, s9, 0
	s_mov_b32 s15, 0x800000
	v_mov_b32_e32 v3, 0
	s_mov_b32 s16, s2
	s_branch .LBB0_1147

.LBB0_1192:
	s_cmp_gt_i32 s34, 12
	s_cselect_b64 s[0:1], -1, 0
	s_cmp_lt_i32 s35, 12
	s_cselect_b64 s[4:5], -1, 0
	s_or_b64 s[0:1], s[0:1], s[4:5]
	s_and_b64 vcc, exec, s[0:1]
	s_cbranch_vccnz .LBB0_1246
	s_mov_b64 s[0:1], 0
	s_add_u32 s4, s86, s0
	s_addc_u32 s5, s87, s1
	s_add_u32 s6, s4, 0x2830000
	s_load_dword s3, s[92:93], 0xd8
	s_addc_u32 s7, s5, 0
	s_add_u32 s0, s4, 0xac00000
	s_addc_u32 s1, s5, 0
	s_add_u32 s8, s4, 0x4c00000
	s_addc_u32 s9, s5, 0
	s_waitcnt lgkmcnt(0)
	s_and_b32 s10, s3, 7
	s_cmp_lg_u32 s10, 0
	s_cselect_b64 s[12:13], -1, 0
	s_cmp_lt_i32 s3, 8
	s_cselect_b64 s[14:15], -1, 0
	s_lshl_b32 s10, s2, 5
	s_or_b64 s[12:13], s[14:15], s[12:13]
	s_lshr_b32 s33, s3, 3
	s_ashr_i32 s34, s2, 3
	s_and_b32 s50, s10, 0xe0
	s_add_u32 s51, s4, 0x6c00000
	s_addc_u32 s52, s5, 0
	s_add_u32 s53, s4, 0xa00000
	s_mov_b32 s11, 0
	s_addc_u32 s54, s5, 0
	v_and_b32_e32 v187, 0x3ff, v0
	s_movk_i32 s55, 0x100
	v_mov_b32_e32 v149, 0
	s_add_i32 s56, 0, 0x10000
	s_add_i32 s57, 0, 0x14000
	s_mov_b64 s[14:15], 0x80
	s_add_i32 s58, 0, 0x18000
	s_add_i32 s59, 0, 0x1c000
	s_movk_i32 s60, 0x3c0
	s_mov_b64 s[16:17], 0x6c40080
	s_mov_b64 s[18:19], 0xa00100
	s_mov_b64 s[20:21], 0x6c00100
	s_mov_b64 s[22:23], 0xa40100
	s_mov_b64 s[24:25], 0x6c40100
	s_mov_b64 s[26:27], 0xa00180
	s_mov_b64 s[28:29], 0x6c00180
	s_mov_b64 s[30:31], 0xa40180
	s_mov_b64 s[36:37], 0x780
	v_mov_b32_e32 v193, 0x358637bd
	s_mov_b32 s61, 0x800000
	v_mov_b32_e32 v228, 1
	s_mov_b32 s62, 0
	s_branch .LBB0_1195
